# P0 FFN gate/up weight transposes: the eight per-row norm-gain loads issued together (was four dependent pairs)
# baseline (speedup 1.0000x reference)
.LBB0_17:
	s_andn2_b64 vcc, exec, s[0:1]
	s_cbranch_vccnz .LBB0_31
	s_and_b32 s0, s87, 0x7fc0
	s_add_i32 s2, s0, 0xffffb600
	s_and_b32 s50, s72, 0x7e0
	v_or_b32_e32 v42, s2, v38
	s_lshl_b32 s0, s50, 2
	s_mov_b32 s1, s3
	v_or_b32_e32 v6, 8, v42
	v_mov_b32_e32 v7, v43
	v_lshl_add_u64 v[2:3], v[54:55], 0, s[0:1]
	v_lshlrev_b64 v[4:5], 13, v[42:43]
	v_lshlrev_b64 v[6:7], 13, v[6:7]
	v_lshl_add_u64 v[4:5], v[2:3], 0, v[4:5]
	v_lshl_add_u64 v[6:7], v[2:3], 0, v[6:7]
	global_load_dwordx4 v[26:29], v[4:5], off
	global_load_dwordx4 v[30:33], v[6:7], off
	v_or_b32_e32 v4, 16, v42
	v_mov_b32_e32 v5, v43
	v_or_b32_e32 v6, 24, v42
	v_mov_b32_e32 v7, v43
	v_lshlrev_b64 v[4:5], 13, v[4:5]
	v_lshlrev_b64 v[6:7], 13, v[6:7]
	v_lshl_add_u64 v[4:5], v[2:3], 0, v[4:5]
	v_lshl_add_u64 v[6:7], v[2:3], 0, v[6:7]
	global_load_dwordx4 v[18:21], v[4:5], off
	global_load_dwordx4 v[22:25], v[6:7], off
	v_or_b32_e32 v4, 32, v42
	v_mov_b32_e32 v5, v43
	v_or_b32_e32 v6, 40, v42
	v_mov_b32_e32 v7, v43
	v_lshlrev_b64 v[4:5], 13, v[4:5]
	v_lshlrev_b64 v[6:7], 13, v[6:7]
	v_lshl_add_u64 v[4:5], v[2:3], 0, v[4:5]
	v_lshl_add_u64 v[6:7], v[2:3], 0, v[6:7]
	global_load_dwordx4 v[10:13], v[4:5], off
	global_load_dwordx4 v[14:17], v[6:7], off
	v_or_b32_e32 v4, 48, v42
	v_mov_b32_e32 v5, v43
	v_or_b32_e32 v6, 56, v42
	v_mov_b32_e32 v7, v43
	v_lshlrev_b64 v[4:5], 13, v[4:5]
	v_lshlrev_b64 v[6:7], 13, v[6:7]
	v_lshl_add_u64 v[4:5], v[2:3], 0, v[4:5]
	v_lshl_add_u64 v[6:7], v[2:3], 0, v[6:7]
	global_load_dwordx4 v[2:5], v[4:5], off
	s_nop 0
	global_load_dwordx4 v[6:9], v[6:7], off
	v_cndmask_b32_e64 v34, 0, 1, s[46:47]
	v_cmp_ne_u32_e64 s[0:1], 1, v34
	s_andn2_b64 vcc, exec, s[46:47]
	v_add_u32_e32 v66, s2, v38
	s_cbranch_vccnz .LBB0_74
	v_mov_b32_e32 v67, v43
	v_lshl_add_u64 v[34:35], v[42:43], 2, s[44:45]
	v_lshl_add_u64 v[36:37], v[66:67], 2, s[44:45]
	global_load_dword v120, v[34:35], off
	global_load_dword v122, v[36:37], off offset:32
	global_load_dword v124, v[36:37], off offset:64
	global_load_dword v126, v[36:37], off offset:96
	global_load_dword v128, v[36:37], off offset:128
	global_load_dword v130, v[36:37], off offset:160
	global_load_dword v132, v[36:37], off offset:192
	global_load_dword v134, v[36:37], off offset:224
	s_waitcnt vmcnt(6)
	v_pk_mul_f32 v[68:69], v[28:29], v[120:121] op_sel_hi:[1,0]
	v_pk_mul_f32 v[70:71], v[26:27], v[120:121] op_sel_hi:[1,0]
	v_pk_mul_f32 v[36:37], v[32:33], v[122:123] op_sel_hi:[1,0]
	v_pk_mul_f32 v[34:35], v[30:31], v[122:123] op_sel_hi:[1,0]
	s_cbranch_execnz .LBB0_21

.LBB0_21:
	s_and_b64 vcc, exec, s[0:1]
	ds_write2_b32 v79, v70, v71 offset1:1
	ds_write2_b32 v79, v68, v69 offset0:2 offset1:3
	ds_write2_b32 v80, v34, v35 offset1:1
	ds_write2_b32 v81, v36, v37 offset1:1
	s_cbranch_vccnz .LBB0_75
	s_waitcnt vmcnt(4)
	v_pk_mul_f32 v[30:31], v[20:21], v[124:125] op_sel_hi:[1,0]
	v_pk_mul_f32 v[32:33], v[18:19], v[124:125] op_sel_hi:[1,0]
	v_pk_mul_f32 v[28:29], v[24:25], v[126:127] op_sel_hi:[1,0]
	v_pk_mul_f32 v[26:27], v[22:23], v[126:127] op_sel_hi:[1,0]
	s_cbranch_execnz .LBB0_24

.LBB0_24:
	s_and_b64 vcc, exec, s[0:1]
	s_waitcnt vmcnt(6)
	ds_write2_b32 v82, v32, v33 offset1:1
	ds_write2_b32 v83, v30, v31 offset1:1
	ds_write2_b32 v84, v26, v27 offset1:1
	ds_write2_b32 v85, v28, v29 offset1:1
	s_cbranch_vccnz .LBB0_76
	s_waitcnt vmcnt(2)
	v_pk_mul_f32 v[22:23], v[12:13], v[128:129] op_sel_hi:[1,0]
	v_pk_mul_f32 v[24:25], v[10:11], v[128:129] op_sel_hi:[1,0]
	v_pk_mul_f32 v[20:21], v[16:17], v[130:131] op_sel_hi:[1,0]
	v_pk_mul_f32 v[18:19], v[14:15], v[130:131] op_sel_hi:[1,0]
	s_cbranch_execnz .LBB0_27

.LBB0_27:
	v_add_u32_e32 v26, v1, v75
	s_waitcnt vmcnt(3)
	v_add_u32_e32 v10, 0x420, v26
	ds_write2_b32 v26, v24, v25 offset1:1
	ds_write2_b32 v26, v22, v23 offset0:2 offset1:3
	ds_write2_b32 v10, v18, v19 offset1:1
	v_add_u32_e32 v10, 0x428, v26
	s_and_b64 vcc, exec, s[0:1]
	ds_write2_b32 v10, v20, v21 offset1:1
	s_cbranch_vccnz .LBB0_77
	s_waitcnt vmcnt(0)
	v_pk_mul_f32 v[14:15], v[4:5], v[132:133] op_sel_hi:[1,0]
	v_pk_mul_f32 v[16:17], v[2:3], v[132:133] op_sel_hi:[1,0]
	v_pk_mul_f32 v[12:13], v[8:9], v[134:135] op_sel_hi:[1,0]
	v_pk_mul_f32 v[10:11], v[6:7], v[134:135] op_sel_hi:[1,0]
	s_cbranch_execnz .LBB0_30
